# XCD barrier: non-last arrivers issue the acquire invalidate before polling the generation word instead of after the release is seen
# speedup vs baseline: 1.0284x; 1.0119x over previous
.LBB0_56:
	s_or_b64 exec, exec, s[10:11]
	v_cvt_f32_u32_e32 v4, v2
	s_waitcnt vmcnt(0)
	v_readfirstlane_b32 s3, v3
	v_sub_u32_e32 v3, 0, v2
	v_rcp_iflag_f32_e32 v4, v4
	v_add_u32_e32 v5, s3, v1
	v_mul_f32_e32 v4, 0x4f7ffffe, v4
	v_cvt_u32_f32_e32 v4, v4
	v_mul_lo_u32 v1, v3, v4
	v_mul_hi_u32 v1, v4, v1
	v_add_u32_e32 v1, v4, v1
	v_mul_hi_u32 v1, v5, v1
	v_mul_lo_u32 v3, v1, v2
	v_sub_u32_e32 v3, v5, v3
	v_add_u32_e32 v4, 1, v1
	v_cmp_ge_u32_e32 vcc, v3, v2
	s_nop 1
	v_cndmask_b32_e32 v1, v1, v4, vcc
	v_sub_u32_e32 v4, v3, v2
	v_cndmask_b32_e32 v3, v3, v4, vcc
	v_add_u32_e32 v4, 1, v1
	v_cmp_ge_u32_e32 vcc, v3, v2
	v_add_u32_e32 v3, 1, v5
	s_nop 0
	v_cndmask_b32_e32 v1, v1, v4, vcc
	v_mul_lo_u32 v4, v2, v1
	v_add_u32_e32 v2, v4, v2
	v_cmp_ne_u32_e32 vcc, v3, v2
	s_and_saveexec_b64 s[8:9], vcc
	s_xor_b64 s[8:9], exec, s[8:9]
	s_cbranch_execz .LBB0_70
	s_waitcnt lgkmcnt(0)
	v_mov_b32_e32 v0, 0x2000
	buffer_inv sc1
	global_load_dword v0, v0, s[6:7] offset:1024 sc1
	s_add_u32 s14, s6, 0x2400
	s_addc_u32 s15, s7, 0
	s_waitcnt vmcnt(0)
	v_cmp_eq_u32_e32 vcc, v0, v1
	s_and_saveexec_b64 s[10:11], vcc
	s_cbranch_execz .LBB0_69
	s_add_u32 s12, s4, 0x11080200
	s_addc_u32 s13, s5, 0
	s_mov_b32 s3, 1
	s_mov_b64 s[16:17], 0
	v_mov_b32_e32 v0, 0
	s_branch .LBB0_60

.LBB0_69:
	s_or_b64 exec, exec, s[10:11]
	s_waitcnt vmcnt(0)
	s_waitcnt vmcnt(0)

.LBB0_600:
	s_or_b64 exec, exec, s[14:15]
	v_cvt_f32_u32_e32 v4, v2
	s_waitcnt vmcnt(0)
	v_readfirstlane_b32 s0, v3
	v_sub_u32_e32 v3, 0, v2
	v_rcp_iflag_f32_e32 v4, v4
	v_add_u32_e32 v5, s0, v1
	v_mul_f32_e32 v4, 0x4f7ffffe, v4
	v_cvt_u32_f32_e32 v4, v4
	v_mul_lo_u32 v1, v3, v4
	v_mul_hi_u32 v1, v4, v1
	v_add_u32_e32 v1, v4, v1
	v_mul_hi_u32 v1, v5, v1
	v_mul_lo_u32 v3, v1, v2
	v_sub_u32_e32 v3, v5, v3
	v_add_u32_e32 v4, 1, v1
	v_cmp_ge_u32_e32 vcc, v3, v2
	s_nop 1
	v_cndmask_b32_e32 v1, v1, v4, vcc
	v_sub_u32_e32 v4, v3, v2
	v_cndmask_b32_e32 v3, v3, v4, vcc
	v_add_u32_e32 v4, 1, v1
	v_cmp_ge_u32_e32 vcc, v3, v2
	v_add_u32_e32 v3, 1, v5
	s_nop 0
	v_cndmask_b32_e32 v1, v1, v4, vcc
	v_mul_lo_u32 v4, v2, v1
	v_add_u32_e32 v2, v4, v2
	v_cmp_ne_u32_e32 vcc, v3, v2
	s_and_saveexec_b64 s[0:1], vcc
	s_xor_b64 s[12:13], exec, s[0:1]
	s_cbranch_execz .LBB0_614
	s_waitcnt lgkmcnt(0)
	buffer_inv sc1
	global_load_dword v0, v218, s[10:11] offset:1024 sc1
	s_add_u32 s18, s10, 0x2400
	s_addc_u32 s19, s11, 0
	s_waitcnt vmcnt(0)
	v_cmp_eq_u32_e32 vcc, v0, v1
	s_and_saveexec_b64 s[14:15], vcc
	s_cbranch_execz .LBB0_613
	s_add_u32 s16, s8, 0x11080200
	s_addc_u32 s17, s9, 0
	s_mov_b32 s0, 1
	s_mov_b64 s[20:21], 0
	s_branch .LBB0_604

.LBB0_613:
	s_or_b64 exec, exec, s[14:15]
	s_waitcnt vmcnt(0)
	s_waitcnt vmcnt(0)

.LBB0_1275:
	s_or_b64 exec, exec, s[18:19]
	v_cvt_f32_u32_e32 v4, v2
	s_waitcnt vmcnt(0)
	v_readfirstlane_b32 s0, v3
	v_sub_u32_e32 v3, 0, v2
	v_rcp_iflag_f32_e32 v4, v4
	v_add_u32_e32 v5, s0, v1
	v_mul_f32_e32 v4, 0x4f7ffffe, v4
	v_cvt_u32_f32_e32 v4, v4
	v_mul_lo_u32 v1, v3, v4
	v_mul_hi_u32 v1, v4, v1
	v_add_u32_e32 v1, v4, v1
	v_mul_hi_u32 v1, v5, v1
	v_mul_lo_u32 v3, v1, v2
	v_sub_u32_e32 v3, v5, v3
	v_add_u32_e32 v4, 1, v1
	v_cmp_ge_u32_e32 vcc, v3, v2
	s_nop 1
	v_cndmask_b32_e32 v1, v1, v4, vcc
	v_sub_u32_e32 v4, v3, v2
	v_cndmask_b32_e32 v3, v3, v4, vcc
	v_add_u32_e32 v4, 1, v1
	v_cmp_ge_u32_e32 vcc, v3, v2
	v_add_u32_e32 v3, 1, v5
	s_nop 0
	v_cndmask_b32_e32 v1, v1, v4, vcc
	v_mul_lo_u32 v4, v2, v1
	v_add_u32_e32 v2, v4, v2
	v_cmp_ne_u32_e32 vcc, v3, v2
	s_and_saveexec_b64 s[0:1], vcc
	s_xor_b64 s[16:17], exec, s[0:1]
	s_cbranch_execz .LBB0_1289
	s_waitcnt lgkmcnt(0)
	buffer_inv sc1
	global_load_dword v0, v218, s[14:15] offset:1024 sc1
	s_add_u32 s22, s14, 0x2400
	s_addc_u32 s23, s15, 0
	s_waitcnt vmcnt(0)
	v_cmp_eq_u32_e32 vcc, v0, v1
	s_and_saveexec_b64 s[18:19], vcc
	s_cbranch_execz .LBB0_1288
	s_add_u32 s20, s12, 0x11080200
	s_addc_u32 s21, s13, 0
	s_mov_b32 s0, 1
	s_mov_b64 s[24:25], 0
	s_branch .LBB0_1279

.LBB0_1288:
	s_or_b64 exec, exec, s[18:19]
	s_waitcnt vmcnt(0)
	s_waitcnt vmcnt(0)
